# SwiGLU epilogue regenerated with packed f32 mul/add (same op order), 4 pairs interleaved, no hazard nops
# speedup vs baseline: 1.0209x; 1.0023x over previous
.LBB0_938:
	v_lshl_or_b32 v142, s24, 7, v146
	v_lshl_add_u32 v148, s26, 8, v144
	v_ashrrev_i32_e32 v143, 31, v142
	v_mov_b64_e32 v[140:141], s[52:53]
	v_lshlrev_b64 v[142:143], 1, v[142:143]
	v_readlane_b32 s78, v252, 4
	s_andn2_b64 vcc, exec, s[8:9]
	v_readlane_b32 s79, v252, 5
	s_mov_b32 s98, 0xbfb8aa3b
	v_pk_mul_f32 v[152:153], v[126:127], s[98:99] op_sel_hi:[1,0]
	v_pk_mul_f32 v[154:155], v[128:129], s[98:99] op_sel_hi:[1,0]
	v_pk_mul_f32 v[156:157], v[118:119], s[98:99] op_sel_hi:[1,0]
	v_pk_mul_f32 v[158:159], v[120:121], s[98:99] op_sel_hi:[1,0]
	v_exp_f32_e32 v152, v152
	v_exp_f32_e32 v153, v153
	v_exp_f32_e32 v154, v154
	v_exp_f32_e32 v155, v155
	v_exp_f32_e32 v156, v156
	v_exp_f32_e32 v157, v157
	v_exp_f32_e32 v158, v158
	v_exp_f32_e32 v159, v159
	v_mov_b32_e32 v170, v148
	v_mad_i64_i32 v[168:169], s[4:5], v170, s70, v[140:141]
	v_pk_add_f32 v[152:153], v[152:153], 1.0 op_sel_hi:[1,0]
	v_pk_add_f32 v[154:155], v[154:155], 1.0 op_sel_hi:[1,0]
	v_pk_add_f32 v[156:157], v[156:157], 1.0 op_sel_hi:[1,0]
	v_pk_add_f32 v[158:159], v[158:159], 1.0 op_sel_hi:[1,0]
	v_rcp_f32_e32 v152, v152
	v_rcp_f32_e32 v153, v153
	v_rcp_f32_e32 v154, v154
	v_rcp_f32_e32 v155, v155
	v_rcp_f32_e32 v156, v156
	v_rcp_f32_e32 v157, v157
	v_rcp_f32_e32 v158, v158
	v_rcp_f32_e32 v159, v159
	v_lshl_add_u64 v[168:169], v[168:169], 0, v[142:143]
	v_pk_mul_f32 v[152:153], v[126:127], v[152:153]
	v_pk_mul_f32 v[154:155], v[128:129], v[154:155]
	v_pk_mul_f32 v[156:157], v[118:119], v[156:157]
	v_pk_mul_f32 v[158:159], v[120:121], v[158:159]
	v_pk_mul_f32 v[152:153], v[152:153], v[122:123]
	v_pk_mul_f32 v[154:155], v[154:155], v[124:125]
	v_pk_mul_f32 v[156:157], v[156:157], v[114:115]
	v_pk_mul_f32 v[158:159], v[158:159], v[116:117]
	v_cvt_pk_bf16_f32 v160, v152, v153
	v_cvt_pk_bf16_f32 v161, v154, v155
	v_cvt_pk_bf16_f32 v162, v156, v157
	v_cvt_pk_bf16_f32 v163, v158, v159
	global_store_dwordx4 v[168:169], v[160:163], off sc1
	v_pk_mul_f32 v[152:153], v[110:111], s[98:99] op_sel_hi:[1,0]
	v_pk_mul_f32 v[154:155], v[112:113], s[98:99] op_sel_hi:[1,0]
	v_pk_mul_f32 v[156:157], v[102:103], s[98:99] op_sel_hi:[1,0]
	v_pk_mul_f32 v[158:159], v[104:105], s[98:99] op_sel_hi:[1,0]
	v_exp_f32_e32 v152, v152
	v_exp_f32_e32 v153, v153
	v_exp_f32_e32 v154, v154
	v_exp_f32_e32 v155, v155
	v_exp_f32_e32 v156, v156
	v_exp_f32_e32 v157, v157
	v_exp_f32_e32 v158, v158
	v_exp_f32_e32 v159, v159
	v_add_u32_e32 v170, 0x10, v148
	v_mad_i64_i32 v[168:169], s[4:5], v170, s70, v[140:141]
	v_pk_add_f32 v[152:153], v[152:153], 1.0 op_sel_hi:[1,0]
	v_pk_add_f32 v[154:155], v[154:155], 1.0 op_sel_hi:[1,0]
	v_pk_add_f32 v[156:157], v[156:157], 1.0 op_sel_hi:[1,0]
	v_pk_add_f32 v[158:159], v[158:159], 1.0 op_sel_hi:[1,0]
	v_rcp_f32_e32 v152, v152
	v_rcp_f32_e32 v153, v153
	v_rcp_f32_e32 v154, v154
	v_rcp_f32_e32 v155, v155
	v_rcp_f32_e32 v156, v156
	v_rcp_f32_e32 v157, v157
	v_rcp_f32_e32 v158, v158
	v_rcp_f32_e32 v159, v159
	v_lshl_add_u64 v[168:169], v[168:169], 0, v[142:143]
	v_pk_mul_f32 v[152:153], v[110:111], v[152:153]
	v_pk_mul_f32 v[154:155], v[112:113], v[154:155]
	v_pk_mul_f32 v[156:157], v[102:103], v[156:157]
	v_pk_mul_f32 v[158:159], v[104:105], v[158:159]
	v_pk_mul_f32 v[152:153], v[152:153], v[106:107]
	v_pk_mul_f32 v[154:155], v[154:155], v[108:109]
	v_pk_mul_f32 v[156:157], v[156:157], v[98:99]
	v_pk_mul_f32 v[158:159], v[158:159], v[100:101]
	v_cvt_pk_bf16_f32 v164, v152, v153
	v_cvt_pk_bf16_f32 v165, v154, v155
	v_cvt_pk_bf16_f32 v166, v156, v157
	v_cvt_pk_bf16_f32 v167, v158, v159
	global_store_dwordx4 v[168:169], v[164:167], off sc1
	v_pk_mul_f32 v[152:153], v[94:95], s[98:99] op_sel_hi:[1,0]
	v_pk_mul_f32 v[154:155], v[96:97], s[98:99] op_sel_hi:[1,0]
	v_pk_mul_f32 v[156:157], v[86:87], s[98:99] op_sel_hi:[1,0]
	v_pk_mul_f32 v[158:159], v[88:89], s[98:99] op_sel_hi:[1,0]
	v_exp_f32_e32 v152, v152
	v_exp_f32_e32 v153, v153
	v_exp_f32_e32 v154, v154
	v_exp_f32_e32 v155, v155
	v_exp_f32_e32 v156, v156
	v_exp_f32_e32 v157, v157
	v_exp_f32_e32 v158, v158
	v_exp_f32_e32 v159, v159
	v_add_u32_e32 v170, 0x20, v148
	v_mad_i64_i32 v[168:169], s[4:5], v170, s70, v[140:141]
	v_pk_add_f32 v[152:153], v[152:153], 1.0 op_sel_hi:[1,0]
	v_pk_add_f32 v[154:155], v[154:155], 1.0 op_sel_hi:[1,0]
	v_pk_add_f32 v[156:157], v[156:157], 1.0 op_sel_hi:[1,0]
	v_pk_add_f32 v[158:159], v[158:159], 1.0 op_sel_hi:[1,0]
	v_rcp_f32_e32 v152, v152
	v_rcp_f32_e32 v153, v153
	v_rcp_f32_e32 v154, v154
	v_rcp_f32_e32 v155, v155
	v_rcp_f32_e32 v156, v156
	v_rcp_f32_e32 v157, v157
	v_rcp_f32_e32 v158, v158
	v_rcp_f32_e32 v159, v159
	v_lshl_add_u64 v[168:169], v[168:169], 0, v[142:143]
	v_pk_mul_f32 v[152:153], v[94:95], v[152:153]
	v_pk_mul_f32 v[154:155], v[96:97], v[154:155]
	v_pk_mul_f32 v[156:157], v[86:87], v[156:157]
	v_pk_mul_f32 v[158:159], v[88:89], v[158:159]
	v_pk_mul_f32 v[152:153], v[152:153], v[90:91]
	v_pk_mul_f32 v[154:155], v[154:155], v[92:93]
	v_pk_mul_f32 v[156:157], v[156:157], v[82:83]
	v_pk_mul_f32 v[158:159], v[158:159], v[84:85]
	v_cvt_pk_bf16_f32 v160, v152, v153
	v_cvt_pk_bf16_f32 v161, v154, v155
	v_cvt_pk_bf16_f32 v162, v156, v157
	v_cvt_pk_bf16_f32 v163, v158, v159
	global_store_dwordx4 v[168:169], v[160:163], off sc1
	v_pk_mul_f32 v[152:153], v[78:79], s[98:99] op_sel_hi:[1,0]
	v_pk_mul_f32 v[154:155], v[80:81], s[98:99] op_sel_hi:[1,0]
	v_pk_mul_f32 v[156:157], v[70:71], s[98:99] op_sel_hi:[1,0]
	v_pk_mul_f32 v[158:159], v[72:73], s[98:99] op_sel_hi:[1,0]
	v_exp_f32_e32 v152, v152
	v_exp_f32_e32 v153, v153
	v_exp_f32_e32 v154, v154
	v_exp_f32_e32 v155, v155
	v_exp_f32_e32 v156, v156
	v_exp_f32_e32 v157, v157
	v_exp_f32_e32 v158, v158
	v_exp_f32_e32 v159, v159
	v_add_u32_e32 v170, 0x30, v148
	v_mad_i64_i32 v[168:169], s[4:5], v170, s70, v[140:141]
	v_pk_add_f32 v[152:153], v[152:153], 1.0 op_sel_hi:[1,0]
	v_pk_add_f32 v[154:155], v[154:155], 1.0 op_sel_hi:[1,0]
	v_pk_add_f32 v[156:157], v[156:157], 1.0 op_sel_hi:[1,0]
	v_pk_add_f32 v[158:159], v[158:159], 1.0 op_sel_hi:[1,0]
	v_rcp_f32_e32 v152, v152
	v_rcp_f32_e32 v153, v153
	v_rcp_f32_e32 v154, v154
	v_rcp_f32_e32 v155, v155
	v_rcp_f32_e32 v156, v156
	v_rcp_f32_e32 v157, v157
	v_rcp_f32_e32 v158, v158
	v_rcp_f32_e32 v159, v159
	v_lshl_add_u64 v[168:169], v[168:169], 0, v[142:143]
	v_pk_mul_f32 v[152:153], v[78:79], v[152:153]
	v_pk_mul_f32 v[154:155], v[80:81], v[154:155]
	v_pk_mul_f32 v[156:157], v[70:71], v[156:157]
	v_pk_mul_f32 v[158:159], v[72:73], v[158:159]
	v_pk_mul_f32 v[152:153], v[152:153], v[74:75]
	v_pk_mul_f32 v[154:155], v[154:155], v[76:77]
	v_pk_mul_f32 v[156:157], v[156:157], v[66:67]
	v_pk_mul_f32 v[158:159], v[158:159], v[68:69]
	v_cvt_pk_bf16_f32 v164, v152, v153
	v_cvt_pk_bf16_f32 v165, v154, v155
	v_cvt_pk_bf16_f32 v166, v156, v157
	v_cvt_pk_bf16_f32 v167, v158, v159
	global_store_dwordx4 v[168:169], v[164:167], off sc1
	v_pk_mul_f32 v[152:153], v[62:63], s[98:99] op_sel_hi:[1,0]
	v_pk_mul_f32 v[154:155], v[64:65], s[98:99] op_sel_hi:[1,0]
	v_pk_mul_f32 v[156:157], v[54:55], s[98:99] op_sel_hi:[1,0]
	v_pk_mul_f32 v[158:159], v[56:57], s[98:99] op_sel_hi:[1,0]
	v_exp_f32_e32 v152, v152
	v_exp_f32_e32 v153, v153
	v_exp_f32_e32 v154, v154
	v_exp_f32_e32 v155, v155
	v_exp_f32_e32 v156, v156
	v_exp_f32_e32 v157, v157
	v_exp_f32_e32 v158, v158
	v_exp_f32_e32 v159, v159
	v_add_u32_e32 v170, 0x80, v148
	v_mad_i64_i32 v[168:169], s[4:5], v170, s70, v[140:141]
	v_pk_add_f32 v[152:153], v[152:153], 1.0 op_sel_hi:[1,0]
	v_pk_add_f32 v[154:155], v[154:155], 1.0 op_sel_hi:[1,0]
	v_pk_add_f32 v[156:157], v[156:157], 1.0 op_sel_hi:[1,0]
	v_pk_add_f32 v[158:159], v[158:159], 1.0 op_sel_hi:[1,0]
	v_rcp_f32_e32 v152, v152
	v_rcp_f32_e32 v153, v153
	v_rcp_f32_e32 v154, v154
	v_rcp_f32_e32 v155, v155
	v_rcp_f32_e32 v156, v156
	v_rcp_f32_e32 v157, v157
	v_rcp_f32_e32 v158, v158
	v_rcp_f32_e32 v159, v159
	v_lshl_add_u64 v[168:169], v[168:169], 0, v[142:143]
	v_pk_mul_f32 v[152:153], v[62:63], v[152:153]
	v_pk_mul_f32 v[154:155], v[64:65], v[154:155]
	v_pk_mul_f32 v[156:157], v[54:55], v[156:157]
	v_pk_mul_f32 v[158:159], v[56:57], v[158:159]
	v_pk_mul_f32 v[152:153], v[152:153], v[58:59]
	v_pk_mul_f32 v[154:155], v[154:155], v[60:61]
	v_pk_mul_f32 v[156:157], v[156:157], v[50:51]
	v_pk_mul_f32 v[158:159], v[158:159], v[52:53]
	v_cvt_pk_bf16_f32 v160, v152, v153
	v_cvt_pk_bf16_f32 v161, v154, v155
	v_cvt_pk_bf16_f32 v162, v156, v157
	v_cvt_pk_bf16_f32 v163, v158, v159
	global_store_dwordx4 v[168:169], v[160:163], off sc1
	v_pk_mul_f32 v[152:153], v[46:47], s[98:99] op_sel_hi:[1,0]
	v_pk_mul_f32 v[154:155], v[48:49], s[98:99] op_sel_hi:[1,0]
	v_pk_mul_f32 v[156:157], v[38:39], s[98:99] op_sel_hi:[1,0]
	v_pk_mul_f32 v[158:159], v[40:41], s[98:99] op_sel_hi:[1,0]
	v_exp_f32_e32 v152, v152
	v_exp_f32_e32 v153, v153
	v_exp_f32_e32 v154, v154
	v_exp_f32_e32 v155, v155
	v_exp_f32_e32 v156, v156
	v_exp_f32_e32 v157, v157
	v_exp_f32_e32 v158, v158
	v_exp_f32_e32 v159, v159
	v_add_u32_e32 v170, 0x90, v148
	v_mad_i64_i32 v[168:169], s[4:5], v170, s70, v[140:141]
	v_pk_add_f32 v[152:153], v[152:153], 1.0 op_sel_hi:[1,0]
	v_pk_add_f32 v[154:155], v[154:155], 1.0 op_sel_hi:[1,0]
	v_pk_add_f32 v[156:157], v[156:157], 1.0 op_sel_hi:[1,0]
	v_pk_add_f32 v[158:159], v[158:159], 1.0 op_sel_hi:[1,0]
	v_rcp_f32_e32 v152, v152
	v_rcp_f32_e32 v153, v153
	v_rcp_f32_e32 v154, v154
	v_rcp_f32_e32 v155, v155
	v_rcp_f32_e32 v156, v156
	v_rcp_f32_e32 v157, v157
	v_rcp_f32_e32 v158, v158
	v_rcp_f32_e32 v159, v159
	v_lshl_add_u64 v[168:169], v[168:169], 0, v[142:143]
	v_pk_mul_f32 v[152:153], v[46:47], v[152:153]
	v_pk_mul_f32 v[154:155], v[48:49], v[154:155]
	v_pk_mul_f32 v[156:157], v[38:39], v[156:157]
	v_pk_mul_f32 v[158:159], v[40:41], v[158:159]
	v_pk_mul_f32 v[152:153], v[152:153], v[42:43]
	v_pk_mul_f32 v[154:155], v[154:155], v[44:45]
	v_pk_mul_f32 v[156:157], v[156:157], v[34:35]
	v_pk_mul_f32 v[158:159], v[158:159], v[36:37]
	v_cvt_pk_bf16_f32 v164, v152, v153
	v_cvt_pk_bf16_f32 v165, v154, v155
	v_cvt_pk_bf16_f32 v166, v156, v157
	v_cvt_pk_bf16_f32 v167, v158, v159
	global_store_dwordx4 v[168:169], v[164:167], off sc1
	v_pk_mul_f32 v[152:153], v[30:31], s[98:99] op_sel_hi:[1,0]
	v_pk_mul_f32 v[154:155], v[32:33], s[98:99] op_sel_hi:[1,0]
	v_pk_mul_f32 v[156:157], v[22:23], s[98:99] op_sel_hi:[1,0]
	v_pk_mul_f32 v[158:159], v[24:25], s[98:99] op_sel_hi:[1,0]
	v_exp_f32_e32 v152, v152
	v_exp_f32_e32 v153, v153
	v_exp_f32_e32 v154, v154
	v_exp_f32_e32 v155, v155
	v_exp_f32_e32 v156, v156
	v_exp_f32_e32 v157, v157
	v_exp_f32_e32 v158, v158
	v_exp_f32_e32 v159, v159
	v_add_u32_e32 v170, 0xa0, v148
	v_mad_i64_i32 v[168:169], s[4:5], v170, s70, v[140:141]
	v_pk_add_f32 v[152:153], v[152:153], 1.0 op_sel_hi:[1,0]
	v_pk_add_f32 v[154:155], v[154:155], 1.0 op_sel_hi:[1,0]
	v_pk_add_f32 v[156:157], v[156:157], 1.0 op_sel_hi:[1,0]
	v_pk_add_f32 v[158:159], v[158:159], 1.0 op_sel_hi:[1,0]
	v_rcp_f32_e32 v152, v152
	v_rcp_f32_e32 v153, v153
	v_rcp_f32_e32 v154, v154
	v_rcp_f32_e32 v155, v155
	v_rcp_f32_e32 v156, v156
	v_rcp_f32_e32 v157, v157
	v_rcp_f32_e32 v158, v158
	v_rcp_f32_e32 v159, v159
	v_lshl_add_u64 v[168:169], v[168:169], 0, v[142:143]
	v_pk_mul_f32 v[152:153], v[30:31], v[152:153]
	v_pk_mul_f32 v[154:155], v[32:33], v[154:155]
	v_pk_mul_f32 v[156:157], v[22:23], v[156:157]
	v_pk_mul_f32 v[158:159], v[24:25], v[158:159]
	v_pk_mul_f32 v[152:153], v[152:153], v[26:27]
	v_pk_mul_f32 v[154:155], v[154:155], v[28:29]
	v_pk_mul_f32 v[156:157], v[156:157], v[18:19]
	v_pk_mul_f32 v[158:159], v[158:159], v[20:21]
	v_cvt_pk_bf16_f32 v160, v152, v153
	v_cvt_pk_bf16_f32 v161, v154, v155
	v_cvt_pk_bf16_f32 v162, v156, v157
	v_cvt_pk_bf16_f32 v163, v158, v159
	global_store_dwordx4 v[168:169], v[160:163], off sc1
	v_pk_mul_f32 v[152:153], v[14:15], s[98:99] op_sel_hi:[1,0]
	v_pk_mul_f32 v[154:155], v[16:17], s[98:99] op_sel_hi:[1,0]
	v_pk_mul_f32 v[156:157], v[6:7], s[98:99] op_sel_hi:[1,0]
	v_pk_mul_f32 v[158:159], v[8:9], s[98:99] op_sel_hi:[1,0]
	v_exp_f32_e32 v152, v152
	v_exp_f32_e32 v153, v153
	v_exp_f32_e32 v154, v154
	v_exp_f32_e32 v155, v155
	v_exp_f32_e32 v156, v156
	v_exp_f32_e32 v157, v157
	v_exp_f32_e32 v158, v158
	v_exp_f32_e32 v159, v159
	v_add_u32_e32 v170, 0xb0, v148
	v_mad_i64_i32 v[168:169], s[4:5], v170, s70, v[140:141]
	v_pk_add_f32 v[152:153], v[152:153], 1.0 op_sel_hi:[1,0]
	v_pk_add_f32 v[154:155], v[154:155], 1.0 op_sel_hi:[1,0]
	v_pk_add_f32 v[156:157], v[156:157], 1.0 op_sel_hi:[1,0]
	v_pk_add_f32 v[158:159], v[158:159], 1.0 op_sel_hi:[1,0]
	v_rcp_f32_e32 v152, v152
	v_rcp_f32_e32 v153, v153
	v_rcp_f32_e32 v154, v154
	v_rcp_f32_e32 v155, v155
	v_rcp_f32_e32 v156, v156
	v_rcp_f32_e32 v157, v157
	v_rcp_f32_e32 v158, v158
	v_rcp_f32_e32 v159, v159
	v_lshl_add_u64 v[168:169], v[168:169], 0, v[142:143]
	v_pk_mul_f32 v[152:153], v[14:15], v[152:153]
	v_pk_mul_f32 v[154:155], v[16:17], v[154:155]
	v_pk_mul_f32 v[156:157], v[6:7], v[156:157]
	v_pk_mul_f32 v[158:159], v[8:9], v[158:159]
	v_pk_mul_f32 v[152:153], v[152:153], v[10:11]
	v_pk_mul_f32 v[154:155], v[154:155], v[12:13]
	v_pk_mul_f32 v[156:157], v[156:157], v[2:3]
	v_pk_mul_f32 v[158:159], v[158:159], v[4:5]
	v_cvt_pk_bf16_f32 v164, v152, v153
	v_cvt_pk_bf16_f32 v165, v154, v155
	v_cvt_pk_bf16_f32 v166, v156, v157
	v_cvt_pk_bf16_f32 v167, v158, v159
	s_mov_b64 s[4:5], -1
	global_store_dwordx4 v[168:169], v[164:167], off sc1
	s_cbranch_vccnz .LBB0_931
	s_andn2_b64 vcc, exec, s[10:11]
	s_cbranch_vccnz .LBB0_930
	s_barrier
	s_branch .LBB0_930
